# v26 + rwkv_prep token-shift staging: mix vectors of the w/a stages loaded up front with the first row load (one load round trip per stage instead of two), scalar pointer setup hoisted
# speedup vs baseline: 1.0046x; 1.0046x over previous
; __device__ __forceinline__ int tid_() { int t = threadIdx.x; asm volatile("" : "+v"(t)); return t; }
; #define LAS __attribute__((address_space(3)))
; DI float fast_tanh(float x) { return 1.f - 2.f * __builtin_amdgcn_rcpf(1.f + __expf(2.f * x)); }
; DI void unpack8(const v4u u, float (&f)[8]) { f[0] = bflo(u.x); f[1] = bfhi(u.x); f[2] = bflo(u.y); f[3] = bfhi(u.y); f[4] = bflo(u.z); f[5] = bfhi(u.z); f[6] = bflo(u.w); f[7] = bfhi(u.w); }
; DI v4u pack8(const float (&f)[8]) { v4u o; o.x = pk2(f[0], f[1]); o.y = pk2(f[2], f[3]); o.z = pk2(f[4], f[5]); o.w = pk2(f[6], f[7]); return o; }
; DI void rwkv_prep_item(KA a, const int l, LAS unsigned char* lds, const int tile) {
;     ...
;     {   const int tk = tid >> 3, c0 = (tid & 7) * 8, t = t0 + tk; const bool first = (t & (SEQ - 1)) == 0;
;         const bf16* hr = H + (size_t)t * HP;
;         float cu[8], pv[8], o[8];
;         unpack8(*(const v4u*)(hr + C_RWL + c0), cu); if (first) { for (int e = 0; e < 8; ++e) pv[e] = 0.f; } else unpack8(*(const v4u*)(hr - HP + C_RWL + c0), pv);
; #pragma unroll
;         for (int e = 0; e < 8; ++e) o[e] = fast_tanh(cu[e] + (pv[e] - cu[e]) * mu[768 + c0 + e]);
;         *(LAS v4u*)(Aw + tk * PA + c0) = pack8(o);
;         unpack8(*(const v4u*)(hr + C_RAL + c0), cu); if (first) { for (int e = 0; e < 8; ++e) pv[e] = 0.f; } else unpack8(*(const v4u*)(hr - HP + C_RAL + c0), pv);
; #pragma unroll
;         for (int e = 0; e < 8; ++e) o[e] = cu[e] + (pv[e] - cu[e]) * mu[832 + c0 + e];
;         *(LAS v4u*)(Aa + tk * PA + c0) = pack8(o);
; DI void prep_phase(KA a, const int l, LAS unsigned char* lds) {
;     ...
;         for (;;) {
;             __syncthreads();
;             if (tid_() == 0) *(LAS int*)(lds + NSA_ITEM) = (int)atomicAdd(ctr, 1u);
;             __syncthreads();
;             const int it = *(LAS int*)(lds + NSA_ITEM);
;             if (it >= 128 + T / 64) break;
;             if (it < 128) nsa_compress_item(a, l, lds, it); else rwkv_prep_item(a, l, lds, it - 128);
.LBB0_328:
	s_or_b64 exec, exec, s[0:1]
	v_readlane_b32 s0, v254, 6
	s_waitcnt lgkmcnt(0)
	s_barrier
	v_mov_b32_e32 v0, s0
	ds_read_b32 v0, v0
	s_movk_i32 s0, 0x27f
	s_waitcnt lgkmcnt(0)
	v_cmp_lt_i32_e32 vcc, s0, v0
	v_readfirstlane_b32 s60, v0
	s_mov_b64 s[0:1], -1
	s_cbranch_vccnz .LBB0_323
	s_cmpk_gt_i32 s60, 0x7f
	s_cbranch_scc0 .LBB0_469
	v_mov_b32_e32 v18, v232
	s_lshl_b32 s33, s60, 6
	s_addk_i32 s33, 0xe000
	v_ashrrev_i32_e32 v9, 3, v18
	v_and_b32_e32 v11, 7, v18
	v_add_u32_e32 v8, s33, v9
	v_mov_b64_e32 v[0:1], s[16:17]
	s_movk_i32 s0, 0x1c00
	v_mad_i64_i32 v[6:7], s[0:1], v8, s0, v[0:1]
	v_lshlrev_b32_e32 v192, 4, v11
	v_lshl_add_u64 v[4:5], v[6:7], 0, v[192:193]
	s_load_dwordx2 s[2:3], s[12:13], 0x38
	v_readlane_b32 s4, v254, 30
	v_readlane_b32 s5, v254, 31
	s_lshl_b64 s[4:5], s[4:5], 2
	v_lshlrev_b32_e32 v255, 5, v11
	s_waitcnt lgkmcnt(0)
	s_add_u32 s4, s2, s4
	s_addc_u32 s5, s3, s5
	s_barrier
	global_load_dwordx4 v[0:3], v[4:5], off offset:3616
	global_load_dwordx4 v[208:211], v255, s[4:5] offset:3088
	global_load_dwordx4 v[212:215], v255, s[4:5] offset:3072
	global_load_dwordx4 v[216:219], v255, s[4:5] offset:3344
	global_load_dwordx4 v[220:223], v255, s[4:5] offset:3328
	v_and_b32_e32 v8, 0x7ff, v8
	v_cmp_ne_u32_e64 s[0:1], 0, v8
	v_mov_b32_e32 v8, 0
	v_mov_b32_e32 v19, 0
	v_mov_b32_e32 v17, 0
	v_mov_b32_e32 v16, 0
	v_mov_b32_e32 v15, 0
	v_mov_b32_e32 v14, 0
	v_mov_b32_e32 v13, 0
	v_mov_b32_e32 v12, 0
	v_mov_b32_e32 v10, 0
	s_and_saveexec_b64 s[2:3], s[0:1]
	s_cbranch_execz .LBB0_332
	global_load_dwordx4 v[20:23], v[4:5], off offset:-3552
	s_waitcnt vmcnt(0)
	v_lshlrev_b32_e32 v19, 16, v20
	v_and_b32_e32 v17, 0xffff0000, v20
	v_lshlrev_b32_e32 v16, 16, v21
	v_and_b32_e32 v15, 0xffff0000, v21
	v_lshlrev_b32_e32 v14, 16, v22
	v_and_b32_e32 v13, 0xffff0000, v22
	v_lshlrev_b32_e32 v12, 16, v23
	v_and_b32_e32 v10, 0xffff0000, v23
.LBB0_332:
	s_or_b64 exec, exec, s[2:3]
	v_lshlrev_b32_e32 v24, 3, v11
	v_lshlrev_b32_e32 v192, 2, v24
	s_waitcnt vmcnt(0)
	v_lshlrev_b32_e32 v25, 16, v0
	v_and_b32_e32 v26, 0xffff0000, v0
	v_lshlrev_b32_e32 v27, 16, v1
	v_and_b32_e32 v28, 0xffff0000, v1
	v_lshlrev_b32_e32 v29, 16, v2
	v_and_b32_e32 v30, 0xffff0000, v2
	v_lshlrev_b32_e32 v31, 16, v3
	v_and_b32_e32 v32, 0xffff0000, v3
	v_sub_f32_e32 v14, v14, v29
	v_sub_f32_e32 v13, v13, v30
	v_sub_f32_e32 v17, v17, v26
	v_sub_f32_e32 v15, v15, v28
	v_sub_f32_e32 v19, v19, v25
	v_sub_f32_e32 v16, v16, v27
	v_mul_lo_u32 v9, v9, s75
	s_waitcnt vmcnt(1)
	v_fmac_f32_e32 v29, v14, v208
	v_fmac_f32_e32 v30, v13, v209
	v_add_f32_e32 v0, v29, v29
	v_add_f32_e32 v1, v30, v30
	v_mul_f32_e32 v0, 0x3fb8aa3b, v0
	v_mul_f32_e32 v1, 0x3fb8aa3b, v1
	v_exp_f32_e32 v0, v0
	v_exp_f32_e32 v1, v1
	s_waitcnt vmcnt(0)
	v_fmac_f32_e32 v26, v17, v213
	v_fmac_f32_e32 v28, v15, v215
	v_add_f32_e32 v17, v26, v26
	v_add_f32_e32 v15, v28, v28
	v_mul_f32_e32 v17, 0x3fb8aa3b, v17
	v_mul_f32_e32 v15, 0x3fb8aa3b, v15
	v_exp_f32_e32 v17, v17
	v_exp_f32_e32 v15, v15
	v_add_f32_e32 v0, 1.0, v0
	v_add_f32_e32 v1, 1.0, v1
	v_rcp_f32_e32 v0, v0
	v_rcp_f32_e32 v1, v1
	v_add_f32_e32 v17, 1.0, v17
	v_add_f32_e32 v15, 1.0, v15
	v_rcp_f32_e32 v21, v17
	v_rcp_f32_e32 v17, v15
	v_pk_fma_f32 v[14:15], v[0:1], 2.0, 1.0 op_sel_hi:[1,0,0] neg_lo:[1,0,0] neg_hi:[1,0,0]
	v_sub_f32_e32 v0, v12, v31
	v_sub_f32_e32 v1, v10, v32
	v_fmac_f32_e32 v25, v19, v212
	v_fmac_f32_e32 v27, v16, v214
	v_fmac_f32_e32 v31, v0, v210
	v_fmac_f32_e32 v32, v1, v211
	v_add_f32_e32 v19, v25, v25
	v_add_f32_e32 v16, v27, v27
	v_add_f32_e32 v0, v31, v31
	v_add_f32_e32 v1, v32, v32
	v_mul_f32_e32 v19, 0x3fb8aa3b, v19
	v_mul_f32_e32 v16, 0x3fb8aa3b, v16
	v_mul_f32_e32 v0, 0x3fb8aa3b, v0
	v_mul_f32_e32 v1, 0x3fb8aa3b, v1
	v_exp_f32_e32 v19, v19
	v_exp_f32_e32 v16, v16
	v_exp_f32_e32 v0, v0
	v_exp_f32_e32 v1, v1
	v_add_f32_e32 v19, 1.0, v19
	v_add_f32_e32 v16, 1.0, v16
	v_add_f32_e32 v0, 1.0, v0
	v_add_f32_e32 v1, 1.0, v1
	v_rcp_f32_e32 v20, v19
	v_rcp_f32_e32 v16, v16
	v_rcp_f32_e32 v0, v0
	v_rcp_f32_e32 v1, v1
	v_pk_fma_f32 v[20:21], v[20:21], 2.0, 1.0 op_sel_hi:[1,0,0] neg_lo:[1,0,0] neg_hi:[1,0,0]
	v_pk_fma_f32 v[16:17], v[16:17], 2.0, 1.0 op_sel_hi:[1,0,0] neg_lo:[1,0,0] neg_hi:[1,0,0]
	v_lshlrev_b32_e32 v10, 1, v24
	v_pk_fma_f32 v[12:13], v[0:1], 2.0, 1.0 op_sel_hi:[1,0,0] neg_lo:[1,0,0] neg_hi:[1,0,0]
	v_cvt_pk_bf16_f32 v0, v20, v21
	v_cvt_pk_bf16_f32 v1, v16, v17
	v_cvt_pk_bf16_f32 v2, v14, v15
	v_cvt_pk_bf16_f32 v3, v12, v13
	v_add3_u32 v19, 0, v9, v10
	ds_write_b128 v19, v[0:3]
	global_load_dwordx4 v[0:3], v[4:5], off offset:3744
	v_mov_b32_e32 v9, 0
	v_mov_b32_e32 v12, 0
	v_mov_b32_e32 v13, 0
	v_mov_b32_e32 v14, 0
	v_mov_b32_e32 v15, 0
	v_mov_b32_e32 v16, 0
	v_mov_b32_e32 v17, 0
	s_and_saveexec_b64 s[2:3], s[0:1]
	s_cbranch_execz .LBB0_334
	global_load_dwordx4 v[20:23], v[4:5], off offset:-3424
	s_waitcnt vmcnt(0)
	v_lshlrev_b32_e32 v16, 16, v20
	v_and_b32_e32 v17, 0xffff0000, v20
	v_lshlrev_b32_e32 v14, 16, v21
	v_and_b32_e32 v15, 0xffff0000, v21
	v_lshlrev_b32_e32 v12, 16, v22
	v_and_b32_e32 v13, 0xffff0000, v22
	v_lshlrev_b32_e32 v8, 16, v23
	v_and_b32_e32 v9, 0xffff0000, v23
; #define LAS __attribute__((address_space(3)))
; DI void unpack8(const v4u u, float (&f)[8]) { f[0] = bflo(u.x); f[1] = bfhi(u.x); f[2] = bflo(u.y); f[3] = bfhi(u.y); f[4] = bflo(u.z); f[5] = bfhi(u.z); f[6] = bflo(u.w); f[7] = bfhi(u.w); }
; DI v4u pack8(const float (&f)[8]) { v4u o; o.x = pk2(f[0], f[1]); o.y = pk2(f[2], f[3]); o.z = pk2(f[4], f[5]); o.w = pk2(f[6], f[7]); return o; }
; DI void rwkv_prep_item(KA a, const int l, LAS unsigned char* lds, const int tile) {
;     ...
;         unpack8(*(const v4u*)(hr + C_RAL + c0), cu); if (first) { for (int e = 0; e < 8; ++e) pv[e] = 0.f; } else unpack8(*(const v4u*)(hr - HP + C_RAL + c0), pv);
; #pragma unroll
;         for (int e = 0; e < 8; ++e) o[e] = cu[e] + (pv[e] - cu[e]) * mu[832 + c0 + e];
;         *(LAS v4u*)(Aa + tk * PA + c0) = pack8(o);
;         if (l == 1 && (tid & 7) < 4) { const float* muv = a->in[I_MUV];
;             unpack8(*(const v4u*)(hr + C_VR + c0), cu); if (first) { for (int e = 0; e < 8; ++e) pv[e] = 0.f; } else unpack8(*(const v4u*)(hr - HP + C_VR + c0), pv);
; #pragma unroll
;             for (int e = 0; e < 8; ++e) o[e] = cu[e] + (pv[e] - cu[e]) * muv[c0 + e];
;             *(LAS v4u*)(Av + tk * PA + c0) = pack8(o); }
.LBB0_334:
	s_or_b64 exec, exec, s[2:3]
	v_lshl_add_u64 v[20:21], s[4:5], 0, v[192:193]
	s_waitcnt vmcnt(0)
	v_lshlrev_b32_e32 v24, 16, v0
	v_and_b32_e32 v25, 0xffff0000, v0
	v_lshlrev_b32_e32 v26, 16, v1
	v_and_b32_e32 v27, 0xffff0000, v1
	v_lshlrev_b32_e32 v28, 16, v2
	v_and_b32_e32 v29, 0xffff0000, v2
	v_lshlrev_b32_e32 v30, 16, v3
	v_and_b32_e32 v31, 0xffff0000, v3
	s_nop 0
	v_pk_add_f32 v[12:13], v[12:13], v[28:29] neg_lo:[0,1] neg_hi:[0,1]
	v_pk_add_f32 v[16:17], v[16:17], v[24:25] neg_lo:[0,1] neg_hi:[0,1]
	v_pk_add_f32 v[14:15], v[14:15], v[26:27] neg_lo:[0,1] neg_hi:[0,1]
	v_cmp_gt_u32_e32 vcc, 4, v11
	s_and_b64 s[40:41], s[6:7], vcc
	s_waitcnt vmcnt(1)
	v_pk_fma_f32 v[12:13], v[12:13], v[216:217], v[28:29]
	v_pk_add_f32 v[0:1], v[8:9], v[30:31] neg_lo:[0,1] neg_hi:[0,1]
	s_waitcnt vmcnt(0)
	v_pk_fma_f32 v[16:17], v[16:17], v[220:221], v[24:25]
	v_pk_fma_f32 v[14:15], v[14:15], v[222:223], v[26:27]
	v_pk_fma_f32 v[8:9], v[0:1], v[218:219], v[30:31]
	v_cvt_pk_bf16_f32 v0, v16, v17
	v_cvt_pk_bf16_f32 v1, v14, v15
	v_cvt_pk_bf16_f32 v2, v12, v13
	v_cvt_pk_bf16_f32 v3, v8, v9
	ds_write_b128 v19, v[0:3] offset:9216
	s_and_saveexec_b64 s[2:3], s[40:41]
	s_cbranch_execz .LBB0_338
	v_mov_b32_e32 v11, v193
	v_lshl_add_u64 v[0:1], v[6:7], 0, v[10:11]
	v_add_co_u32_e32 v0, vcc, 0x1000, v0
	v_mov_b32_e32 v6, 0
	s_nop 0
	v_addc_co_u32_e32 v1, vcc, 0, v1, vcc
	global_load_dwordx4 v[0:3], v[0:1], off offset:2704
	v_mov_b32_e32 v7, 0
	v_mov_b32_e32 v8, 0
	v_mov_b32_e32 v9, 0
	v_mov_b32_e32 v10, 0
	v_mov_b32_e32 v11, 0
	v_mov_b32_e32 v12, 0
	v_mov_b32_e32 v13, 0
	s_and_saveexec_b64 s[40:41], s[0:1]
	s_cbranch_execz .LBB0_337
	global_load_dwordx4 v[4:7], v[4:5], off offset:-368
	s_waitcnt vmcnt(0)
	v_lshlrev_b32_e32 v12, 16, v4
	v_and_b32_e32 v13, 0xffff0000, v4
	v_lshlrev_b32_e32 v10, 16, v5
	v_and_b32_e32 v11, 0xffff0000, v5
	v_lshlrev_b32_e32 v8, 16, v6
	v_and_b32_e32 v9, 0xffff0000, v6
	v_lshlrev_b32_e32 v6, 16, v7
	v_and_b32_e32 v7, 0xffff0000, v7
